# P6 per-panel rstd table: 16 partial-sum loads batched (was an 8-step load/wait ladder); P7 conv_fixup hand-written: 4 consecutive columns per lane with 16-byte loads, 3 groups in flight (was one colum
# speedup vs baseline: 1.0685x; 1.0005x over previous
; #define PG8_STAGE(bufoff, gbase, voff) do { _Pragma("unroll") for (int _i = 0; _i < 2; ++_i) \
;         __builtin_amdgcn_global_load_lds((const unsigned*)((const char*)(gbase) + (voff)[_i]), (LAS unsigned*)(lds + (bufoff) + ldsw + _i * 8192), 16, 0, 0); } while (0)
; #define PG8_LDA(dst, b, h) do { _Pragma("unroll") for (int m = 0; m < 4; ++m) _Pragma("unroll") for (int k = 0; k < 2; ++k) dst[m][k] = *(const LAS bf16x8*)(lds + PG8_SA(b, h) + aoff + m * 2048 + k * 1024); } while (0)
; #define PG8_LDB(dst, b, h) do { _Pragma("unroll") for (int n = 0; n < 2; ++n) _Pragma("unroll") for (int k = 0; k < 2; ++k) dst[n][k] = *(const LAS bf16x8*)(lds + PG8_SB(b, h) + boff + n * 2048 + k * 1024); } while (0)
; #define PG8_MMA(ai, bj, At, Bt) do { __builtin_amdgcn_s_setprio(1); _Pragma("unroll") for (int m = 0; m < 4; ++m) _Pragma("unroll") for (int n = 0; n < 2; ++n) _Pragma("unroll") for (int k = 0; k < 2; ++k) \
;         acc[ai][bj][m][n] = __builtin_amdgcn_mfma_f32_16x16x32_bf16(Bt[n][k], At[m][k], acc[ai][bj][m][n], 0, 0, 0); __builtin_amdgcn_s_setprio(0); } while (0)
; #define PG8_BAR __builtin_amdgcn_s_barrier()
; template <class Epi, bool KS0 = false>
; __device__ __forceinline__ void gemm_phase(const int WID, LAS unsigned char* lds, const Gemm g, const StaticOrder& S, const Epi& E) {
;     ...
;         for (int t = 0; t < nt; t += 2) {
;             const bool last = (t == nt - 2);
;             const char* a1 = cA + (size_t)(t + 1) * kstep;
;             const char* a2 = last ? nA : cA + (size_t)(t + 2) * kstep; const char* b2 = last ? nB : cB + (size_t)(t + 2) * kstep;
;             const char* a3 = a2 + kstep; const char* b3 = b2 + kstep;
;             PG8_LDB(B0, 0, 0); PG8_SCHED; PG8_LDA(At, 0, 0); PG8_STAGE(PG8_SA(1, 1), a1 + hstep, voffA);
;             PG8_WAIT_L(8); PG8_BAR; PG8_WAIT_L(0); PG8_MMA(0, 0, At, B0); PG8_BAR; PG8_SCHED;
;             PG8_LDB(B1, 0, 1); PG8_STAGE(PG8_SB(0, 0), b2, voffB);
;             PG8_BAR; PG8_WAIT_L(0); PG8_MMA(0, 1, At, B1); PG8_BAR;
;             PG8_LDA(At, 0, 1); PG8_STAGE(PG8_SA(0, 0), a2, voffA);
;             PG8_BAR; PG8_WAIT_L(0); PG8_MMA(1, 0, At, B0); PG8_BAR; PG8_SCHED;
;             PG8_STAGE(PG8_SB(0, 1), b2 + hstep, voffB);
;             PG8_WAIT_V(6); PG8_BAR; PG8_MMA(1, 1, At, B1); PG8_BAR;
;             PG8_LDB(B0, 1, 0); PG8_SCHED; PG8_LDA(At, 1, 0); PG8_STAGE(PG8_SA(0, 1), a2 + hstep, voffA);
.LBB0_777:
	ds_read_b128 v[156:159], v176
	ds_read_b128 v[160:163], v176 offset:1024
	ds_read_b128 v[164:167], v176 offset:2048
	ds_read_b128 v[168:171], v176 offset:3072
	ds_read_b128 v[180:183], v176 offset:4096
	ds_read_b128 v[184:187], v176 offset:5120
	ds_read_b128 v[188:191], v176 offset:6144
	ds_read_b128 v[192:195], v176 offset:7168
	s_add_u32 s12, s2, 0xfff80080
	s_addc_u32 s13, s3, -1
	s_cmp_eq_u32 s53, 28
	s_cselect_b32 s15, s28, s13
	s_cselect_b32 s14, s29, s12
	s_cselect_b32 s13, s42, s45
	s_cselect_b32 s12, s43, s44
	v_lshl_add_u64 v[196:197], s[2:3], 0, v[144:145]
	s_add_i32 m0, s9, 0xc000
	s_nop 0
	global_load_lds_dwordx4 v[196:197], off
	s_add_i32 m0, s9, 0xe000
	s_nop 0
	global_load_lds_dwordx4 v146, s[2:3]
	s_waitcnt lgkmcnt(8)
	s_barrier
	s_waitcnt lgkmcnt(0)
	v_mfma_f32_16x16x32_bf16 v[128:131], v[108:111], v[156:159], v[128:131]
	v_mfma_f32_16x16x32_bf16 v[124:127], v[136:139], v[156:159], v[124:127]
	v_mfma_f32_16x16x32_bf16 v[116:119], v[108:111], v[164:167], v[116:119]
	v_mfma_f32_16x16x32_bf16 v[112:115], v[136:139], v[164:167], v[112:115]
	v_mfma_f32_16x16x32_bf16 v[104:107], v[108:111], v[180:183], v[104:107]
	v_mfma_f32_16x16x32_bf16 v[96:99], v[136:139], v[180:183], v[96:99]
	v_mfma_f32_16x16x32_bf16 v[88:91], v[108:111], v[188:191], v[88:91]
	v_mfma_f32_16x16x32_bf16 v[24:27], v[136:139], v[188:191], v[24:27]
	v_mfma_f32_16x16x32_bf16 v[128:131], v[132:135], v[160:163], v[128:131]
	v_mfma_f32_16x16x32_bf16 v[124:127], v[152:155], v[160:163], v[124:127]
	v_mfma_f32_16x16x32_bf16 v[116:119], v[132:135], v[168:171], v[116:119]
	v_mfma_f32_16x16x32_bf16 v[112:115], v[152:155], v[168:171], v[112:115]
	v_mfma_f32_16x16x32_bf16 v[104:107], v[132:135], v[184:187], v[104:107]
	v_mfma_f32_16x16x32_bf16 v[96:99], v[152:155], v[184:187], v[96:99]
	v_mfma_f32_16x16x32_bf16 v[88:91], v[132:135], v[192:195], v[88:91]
	v_mfma_f32_16x16x32_bf16 v[24:27], v[152:155], v[192:195], v[24:27]
	s_barrier
	ds_read_b128 v[196:199], v177
	ds_read_b128 v[200:203], v177 offset:1024
	ds_read_b128 v[204:207], v177 offset:2048
	ds_read_b128 v[210:213], v177 offset:3072
	s_add_i32 s55, s63, s26
	v_lshl_add_u64 v[214:215], s[12:13], 0, v[140:141]
	s_mov_b32 m0, s55
	s_nop 0
	global_load_lds_dwordx4 v[214:215], off
	v_lshl_add_u64 v[216:217], s[12:13], 0, v[142:143]
	s_add_i32 m0, s55, 0x2000
	s_nop 0
	global_load_lds_dwordx4 v[216:217], off
	s_barrier
	s_waitcnt lgkmcnt(0)
	v_mfma_f32_16x16x32_bf16 v[12:15], v[196:199], v[156:159], v[12:15]
	v_mfma_f32_16x16x32_bf16 v[120:123], v[204:207], v[156:159], v[120:123]
	s_mov_b32 m0, s9
	v_lshl_add_u64 v[218:219], s[14:15], 0, v[140:141]
	v_mfma_f32_16x16x32_bf16 v[100:103], v[196:199], v[164:167], v[100:103]
	v_mfma_f32_16x16x32_bf16 v[92:95], v[204:207], v[164:167], v[92:95]
	v_mfma_f32_16x16x32_bf16 v[84:87], v[196:199], v[180:183], v[84:87]
	v_mfma_f32_16x16x32_bf16 v[80:83], v[204:207], v[180:183], v[80:83]
	v_mfma_f32_16x16x32_bf16 v[28:31], v[196:199], v[188:191], v[28:31]
	v_mfma_f32_16x16x32_bf16 v[20:23], v[204:207], v[188:191], v[20:23]
	v_mfma_f32_16x16x32_bf16 v[12:15], v[200:203], v[160:163], v[12:15]
	v_mfma_f32_16x16x32_bf16 v[120:123], v[210:213], v[160:163], v[120:123]
	v_mfma_f32_16x16x32_bf16 v[100:103], v[200:203], v[168:171], v[100:103]
	v_mfma_f32_16x16x32_bf16 v[92:95], v[210:213], v[168:171], v[92:95]
	v_mfma_f32_16x16x32_bf16 v[84:87], v[200:203], v[184:187], v[84:87]
	v_mfma_f32_16x16x32_bf16 v[80:83], v[210:213], v[184:187], v[80:83]
	v_mfma_f32_16x16x32_bf16 v[28:31], v[200:203], v[192:195], v[28:31]
	v_mfma_f32_16x16x32_bf16 v[20:23], v[210:213], v[192:195], v[20:23]
	s_barrier
	ds_read_b128 v[156:159], v176 offset:16384
	ds_read_b128 v[160:163], v176 offset:17408
	ds_read_b128 v[164:167], v176 offset:18432
	ds_read_b128 v[168:171], v176 offset:19456
	ds_read_b128 v[180:183], v176 offset:20480
	ds_read_b128 v[184:187], v176 offset:21504
	ds_read_b128 v[188:191], v176 offset:22528
	ds_read_b128 v[192:195], v176 offset:23552
	global_load_lds_dwordx4 v[218:219], off
	v_lshl_add_u64 v[220:221], s[14:15], 0, v[142:143]
	s_mov_b32 m0, s11
	s_nop 0
	global_load_lds_dwordx4 v[220:221], off
	s_waitcnt vmcnt(10)
	s_barrier
	s_waitcnt lgkmcnt(0)
	v_mfma_f32_16x16x32_bf16 v[76:79], v[108:111], v[156:159], v[76:79]
	v_mfma_f32_16x16x32_bf16 v[72:75], v[136:139], v[156:159], v[72:75]
	v_mfma_f32_16x16x32_bf16 v[68:71], v[108:111], v[164:167], v[68:71]
	v_mfma_f32_16x16x32_bf16 v[64:67], v[136:139], v[164:167], v[64:67]
	v_mfma_f32_16x16x32_bf16 v[52:55], v[108:111], v[180:183], v[52:55]
	v_mfma_f32_16x16x32_bf16 v[48:51], v[136:139], v[180:183], v[48:51]
	v_mfma_f32_16x16x32_bf16 v[16:19], v[108:111], v[188:191], v[16:19]
	v_mfma_f32_16x16x32_bf16 v[8:11], v[136:139], v[188:191], v[8:11]
	v_mfma_f32_16x16x32_bf16 v[76:79], v[132:135], v[160:163], v[76:79]
	v_mfma_f32_16x16x32_bf16 v[72:75], v[152:155], v[160:163], v[72:75]
	v_mfma_f32_16x16x32_bf16 v[68:71], v[132:135], v[168:171], v[68:71]
	v_mfma_f32_16x16x32_bf16 v[64:67], v[152:155], v[168:171], v[64:67]
	v_mfma_f32_16x16x32_bf16 v[52:55], v[132:135], v[184:187], v[52:55]
	v_mfma_f32_16x16x32_bf16 v[48:51], v[152:155], v[184:187], v[48:51]
	v_mfma_f32_16x16x32_bf16 v[16:19], v[132:135], v[192:195], v[16:19]
	v_mfma_f32_16x16x32_bf16 v[8:11], v[152:155], v[192:195], v[8:11]
	s_barrier
	v_add_u32_e32 v108, 0x18000, v174
	ds_read_b128 v[132:135], v108 offset:1024
	ds_read_b128 v[136:139], v108 offset:2048
	ds_read_b128 v[152:155], v108 offset:3072
	ds_read_b128 v[108:111], v108
	s_add_u32 s70, s12, 0x80000
	s_addc_u32 s71, s13, 0
	s_add_i32 s55, s64, s26
	s_mov_b32 m0, s55
	s_nop 0
	global_load_lds_dwordx4 v140, s[70:71]
	s_add_i32 m0, s55, 0x2000
	s_nop 0
	global_load_lds_dwordx4 v142, s[70:71]
	s_waitcnt vmcnt(6)
	s_barrier
; #define PG8_STAGE(bufoff, gbase, voff) do { _Pragma("unroll") for (int _i = 0; _i < 2; ++_i) \
;         __builtin_amdgcn_global_load_lds((const unsigned*)((const char*)(gbase) + (voff)[_i]), (LAS unsigned*)(lds + (bufoff) + ldsw + _i * 8192), 16, 0, 0); } while (0)
; #define PG8_LDA(dst, b, h) do { _Pragma("unroll") for (int m = 0; m < 4; ++m) _Pragma("unroll") for (int k = 0; k < 2; ++k) dst[m][k] = *(const LAS bf16x8*)(lds + PG8_SA(b, h) + aoff + m * 2048 + k * 1024); } while (0)
; #define PG8_LDB(dst, b, h) do { _Pragma("unroll") for (int n = 0; n < 2; ++n) _Pragma("unroll") for (int k = 0; k < 2; ++k) dst[n][k] = *(const LAS bf16x8*)(lds + PG8_SB(b, h) + boff + n * 2048 + k * 1024); } while (0)
; #define PG8_MMA(ai, bj, At, Bt) do { __builtin_amdgcn_s_setprio(1); _Pragma("unroll") for (int m = 0; m < 4; ++m) _Pragma("unroll") for (int n = 0; n < 2; ++n) _Pragma("unroll") for (int k = 0; k < 2; ++k) \
;         acc[ai][bj][m][n] = __builtin_amdgcn_mfma_f32_16x16x32_bf16(Bt[n][k], At[m][k], acc[ai][bj][m][n], 0, 0, 0); __builtin_amdgcn_s_setprio(0); } while (0)
; #define PG8_WAIT_V(n) asm volatile("s_waitcnt vmcnt(" #n ")" ::: "memory")
; #define PG8_WAIT_L(n) asm volatile("s_waitcnt lgkmcnt(" #n ")" ::: "memory")
; #define PG8_BAR __builtin_amdgcn_s_barrier()
; #define PG8_SCHED __builtin_amdgcn_sched_barrier(0)
; template <class Epi, bool KS0 = false>
; __device__ __forceinline__ void gemm_phase(const int WID, LAS unsigned char* lds, const Gemm g, const StaticOrder& S, const Epi& E) {
;     ...
;             PG8_WAIT_V(6); PG8_BAR; PG8_MMA(1, 1, At, B1); PG8_BAR;
;             PG8_LDB(B0, 1, 0); PG8_SCHED; PG8_LDA(At, 1, 0); PG8_STAGE(PG8_SA(0, 1), a2 + hstep, voffA);
;             PG8_WAIT_L(8); PG8_BAR; PG8_WAIT_L(0); PG8_MMA(0, 0, At, B0); PG8_BAR; PG8_SCHED;
;             PG8_LDB(B1, 1, 1); PG8_STAGE(PG8_SB(1, 0), b3, voffB);
;             PG8_BAR; PG8_WAIT_L(0); PG8_MMA(0, 1, At, B1); PG8_BAR;
;             PG8_LDA(At, 1, 1); PG8_STAGE(PG8_SA(1, 0), a3, voffA);
;             PG8_BAR; PG8_WAIT_L(0); PG8_MMA(1, 0, At, B0); PG8_BAR; PG8_SCHED;
	v_mfma_f32_16x16x32_bf16 v[60:63], v[196:199], v[156:159], v[60:63]
	v_mfma_f32_16x16x32_bf16 v[56:59], v[204:207], v[156:159], v[56:59]
	s_add_i32 s55, 0, 0x18000
	v_mfma_f32_16x16x32_bf16 v[44:47], v[196:199], v[164:167], v[44:47]
	v_mfma_f32_16x16x32_bf16 v[40:43], v[204:207], v[164:167], v[40:43]
	v_mfma_f32_16x16x32_bf16 v[36:39], v[196:199], v[180:183], v[36:39]
	v_mfma_f32_16x16x32_bf16 v[32:35], v[204:207], v[180:183], v[32:35]
	v_mfma_f32_16x16x32_bf16 v[4:7], v[196:199], v[188:191], v[4:7]
	v_mfma_f32_16x16x32_bf16 v[0:3], v[204:207], v[188:191], v[0:3]
	v_mfma_f32_16x16x32_bf16 v[60:63], v[200:203], v[160:163], v[60:63]
	v_mfma_f32_16x16x32_bf16 v[56:59], v[210:213], v[160:163], v[56:59]
	v_mfma_f32_16x16x32_bf16 v[44:47], v[200:203], v[168:171], v[44:47]
	v_mfma_f32_16x16x32_bf16 v[40:43], v[210:213], v[168:171], v[40:43]
	v_mfma_f32_16x16x32_bf16 v[36:39], v[200:203], v[184:187], v[36:39]
	v_mfma_f32_16x16x32_bf16 v[32:35], v[210:213], v[184:187], v[32:35]
	v_mfma_f32_16x16x32_bf16 v[4:7], v[200:203], v[192:195], v[4:7]
	v_mfma_f32_16x16x32_bf16 v[0:3], v[210:213], v[192:195], v[0:3]
	s_barrier
	ds_read_b128 v[156:159], v176 offset:32768
	ds_read_b128 v[160:163], v176 offset:33792
	ds_read_b128 v[164:167], v176 offset:34816
	ds_read_b128 v[168:171], v176 offset:35840
	ds_read_b128 v[180:183], v176 offset:36864
	ds_read_b128 v[184:187], v176 offset:37888
	ds_read_b128 v[188:191], v176 offset:38912
	ds_read_b128 v[192:195], v176 offset:39936
	s_add_u32 s14, s14, 0x80000
	s_addc_u32 s15, s15, 0
	s_mov_b32 m0, s18
	v_lshl_add_u64 v[196:197], s[14:15], 0, v[140:141]
	global_load_lds_dwordx4 v[196:197], off
	s_mov_b32 m0, s19
	s_nop 0
	global_load_lds_dwordx4 v142, s[14:15]
	s_waitcnt lgkmcnt(8)
	s_barrier
	s_waitcnt lgkmcnt(0)
	v_mfma_f32_16x16x32_bf16 v[128:131], v[108:111], v[156:159], v[128:131]
	v_mfma_f32_16x16x32_bf16 v[124:127], v[136:139], v[156:159], v[124:127]
	v_mfma_f32_16x16x32_bf16 v[116:119], v[108:111], v[164:167], v[116:119]
	v_mfma_f32_16x16x32_bf16 v[112:115], v[136:139], v[164:167], v[112:115]
	v_mfma_f32_16x16x32_bf16 v[104:107], v[108:111], v[180:183], v[104:107]
	v_mfma_f32_16x16x32_bf16 v[96:99], v[136:139], v[180:183], v[96:99]
	v_mfma_f32_16x16x32_bf16 v[88:91], v[108:111], v[188:191], v[88:91]
	v_mfma_f32_16x16x32_bf16 v[24:27], v[136:139], v[188:191], v[24:27]
	v_mfma_f32_16x16x32_bf16 v[128:131], v[132:135], v[160:163], v[128:131]
	v_mfma_f32_16x16x32_bf16 v[124:127], v[152:155], v[160:163], v[124:127]
	v_mfma_f32_16x16x32_bf16 v[116:119], v[132:135], v[168:171], v[116:119]
	v_mfma_f32_16x16x32_bf16 v[112:115], v[152:155], v[168:171], v[112:115]
	v_mfma_f32_16x16x32_bf16 v[104:107], v[132:135], v[184:187], v[104:107]
	v_mfma_f32_16x16x32_bf16 v[96:99], v[152:155], v[184:187], v[96:99]
	v_mfma_f32_16x16x32_bf16 v[88:91], v[132:135], v[192:195], v[88:91]
	v_mfma_f32_16x16x32_bf16 v[24:27], v[152:155], v[192:195], v[24:27]
	s_barrier
	s_add_i32 s14, 0, 0x1c000
	v_add_u32_e32 v179, s14, v174
	ds_read_b128 v[196:199], v179
	ds_read_b128 v[200:203], v179 offset:1024
	ds_read_b128 v[204:207], v179 offset:2048
	ds_read_b128 v[210:213], v179 offset:3072
	s_add_i32 s15, s55, s26
	v_lshl_add_u64 v[214:215], v[214:215], 0, s[50:51]
	s_mov_b32 m0, s15
	s_nop 0
	global_load_lds_dwordx4 v[214:215], off
	v_lshl_add_u64 v[214:215], v[216:217], 0, s[50:51]
	s_add_i32 m0, s15, 0x2000
	s_nop 0
	global_load_lds_dwordx4 v[214:215], off
	s_barrier
	s_waitcnt lgkmcnt(0)
	v_mfma_f32_16x16x32_bf16 v[12:15], v[196:199], v[156:159], v[12:15]
	v_mfma_f32_16x16x32_bf16 v[120:123], v[204:207], v[156:159], v[120:123]
	s_mov_b32 m0, s61
	v_lshl_add_u64 v[214:215], v[218:219], 0, s[50:51]
	v_mfma_f32_16x16x32_bf16 v[100:103], v[196:199], v[164:167], v[100:103]
	v_mfma_f32_16x16x32_bf16 v[92:95], v[204:207], v[164:167], v[92:95]
	v_mfma_f32_16x16x32_bf16 v[84:87], v[196:199], v[180:183], v[84:87]
	v_mfma_f32_16x16x32_bf16 v[80:83], v[204:207], v[180:183], v[80:83]
	v_mfma_f32_16x16x32_bf16 v[28:31], v[196:199], v[188:191], v[28:31]
	v_mfma_f32_16x16x32_bf16 v[20:23], v[204:207], v[188:191], v[20:23]
	v_mfma_f32_16x16x32_bf16 v[12:15], v[200:203], v[160:163], v[12:15]
	v_mfma_f32_16x16x32_bf16 v[120:123], v[210:213], v[160:163], v[120:123]
	v_mfma_f32_16x16x32_bf16 v[100:103], v[200:203], v[168:171], v[100:103]
	v_mfma_f32_16x16x32_bf16 v[92:95], v[210:213], v[168:171], v[92:95]
	v_mfma_f32_16x16x32_bf16 v[84:87], v[200:203], v[184:187], v[84:87]
	v_mfma_f32_16x16x32_bf16 v[80:83], v[210:213], v[184:187], v[80:83]
	v_mfma_f32_16x16x32_bf16 v[28:31], v[200:203], v[192:195], v[28:31]
	v_mfma_f32_16x16x32_bf16 v[20:23], v[210:213], v[192:195], v[20:23]
	s_barrier
	ds_read_b128 v[156:159], v176 offset:49152
	ds_read_b128 v[160:163], v176 offset:50176
	ds_read_b128 v[164:167], v176 offset:51200
	ds_read_b128 v[168:171], v176 offset:52224
	ds_read_b128 v[180:183], v176 offset:53248
	ds_read_b128 v[184:187], v176 offset:54272
	ds_read_b128 v[188:191], v176 offset:55296
	ds_read_b128 v[192:195], v176 offset:56320
	global_load_lds_dwordx4 v[214:215], off
	v_lshl_add_u64 v[214:215], v[220:221], 0, s[50:51]
	s_mov_b32 m0, s62
	s_nop 0
	global_load_lds_dwordx4 v[214:215], off
	s_waitcnt vmcnt(10)
	s_barrier
; #define LAS __attribute__((address_space(3)))
; #define PG8_STAGE(bufoff, gbase, voff) do { _Pragma("unroll") for (int _i = 0; _i < 2; ++_i) \
;         __builtin_amdgcn_global_load_lds((const unsigned*)((const char*)(gbase) + (voff)[_i]), (LAS unsigned*)(lds + (bufoff) + ldsw + _i * 8192), 16, 0, 0); } while (0)
; #define PG8_LDA(dst, b, h) do { _Pragma("unroll") for (int m = 0; m < 4; ++m) _Pragma("unroll") for (int k = 0; k < 2; ++k) dst[m][k] = *(const LAS bf16x8*)(lds + PG8_SA(b, h) + aoff + m * 2048 + k * 1024); } while (0)
; #define PG8_MMA(ai, bj, At, Bt) do { __builtin_amdgcn_s_setprio(1); _Pragma("unroll") for (int m = 0; m < 4; ++m) _Pragma("unroll") for (int n = 0; n < 2; ++n) _Pragma("unroll") for (int k = 0; k < 2; ++k) \
;         acc[ai][bj][m][n] = __builtin_amdgcn_mfma_f32_16x16x32_bf16(Bt[n][k], At[m][k], acc[ai][bj][m][n], 0, 0, 0); __builtin_amdgcn_s_setprio(0); } while (0)
; #define PG8_WAIT_V(n) asm volatile("s_waitcnt vmcnt(" #n ")" ::: "memory")
; template <class Epi, bool KS0 = false>
; __device__ __forceinline__ void gemm_phase(const int WID, LAS unsigned char* lds, const Gemm g, const StaticOrder& S, const Epi& E) {
;     ...
;             PG8_BAR; PG8_WAIT_L(0); PG8_MMA(0, 1, At, B1); PG8_BAR;
;             PG8_LDA(At, 1, 1); PG8_STAGE(PG8_SA(1, 0), a3, voffA);
;             PG8_BAR; PG8_WAIT_L(0); PG8_MMA(1, 0, At, B0); PG8_BAR; PG8_SCHED;
;             PG8_STAGE(PG8_SB(1, 1), b3 + hstep, voffB);
;             PG8_WAIT_V(6); PG8_BAR; PG8_MMA(1, 1, At, B1); PG8_BAR;
;     __device__ __forceinline__ void operator()(f32x4 (&acc)[2][2][4][2], const Unit& u, int wr, int wc, int fr, int fq) const {
;         const int rowt = u.pm * BM + wr * 64 + fr, cl0 = wc * 32 + 4 * fq, wv = wr * 4 + wc, ln = fq * 16 + fr;
;         float cwr[4];
; #pragma unroll
;         for (int i = 0; i < 4; ++i) { const float* srcp = (i < 3) ? (cw + (size_t)i * FF2) : cb; cwr[i] = srcp[(ln >> 5) * FF + u.pn * HALF + wc * 32 + (ln & 31)]; }
;         {
;             LAS float* myr = rsl + wv * 128; LAS int* mypm = (LAS int*)(rsl + 1024) + wv;
;             if (__builtin_amdgcn_readfirstlane(*mypm) != u.pm) {
; #pragma unroll
;                 for (int ai = 0; ai < 2; ++ai)
; #pragma unroll
;                     for (int m = 0; m < 4; ++m) { const float r_ = row_rstd(ssq_in, rowt + ai * HALF + m * 16, fq); if (fq == 0) myr[(ai * 4 + m) * 16 + fr] = r_; }
	s_waitcnt lgkmcnt(0)
	v_mfma_f32_16x16x32_bf16 v[76:79], v[108:111], v[156:159], v[76:79]
	v_mfma_f32_16x16x32_bf16 v[72:75], v[136:139], v[156:159], v[72:75]
	v_mfma_f32_16x16x32_bf16 v[68:71], v[108:111], v[164:167], v[68:71]
	v_mfma_f32_16x16x32_bf16 v[64:67], v[136:139], v[164:167], v[64:67]
	v_mfma_f32_16x16x32_bf16 v[52:55], v[108:111], v[180:183], v[52:55]
	v_mfma_f32_16x16x32_bf16 v[48:51], v[136:139], v[180:183], v[48:51]
	v_mfma_f32_16x16x32_bf16 v[16:19], v[108:111], v[188:191], v[16:19]
	v_mfma_f32_16x16x32_bf16 v[8:11], v[136:139], v[188:191], v[8:11]
	v_mfma_f32_16x16x32_bf16 v[76:79], v[132:135], v[160:163], v[76:79]
	v_mfma_f32_16x16x32_bf16 v[72:75], v[152:155], v[160:163], v[72:75]
	v_mfma_f32_16x16x32_bf16 v[68:71], v[132:135], v[168:171], v[68:71]
	v_mfma_f32_16x16x32_bf16 v[64:67], v[152:155], v[168:171], v[64:67]
	v_mfma_f32_16x16x32_bf16 v[52:55], v[132:135], v[184:187], v[52:55]
	v_mfma_f32_16x16x32_bf16 v[48:51], v[152:155], v[184:187], v[48:51]
	v_mfma_f32_16x16x32_bf16 v[16:19], v[132:135], v[192:195], v[16:19]
	v_mfma_f32_16x16x32_bf16 v[8:11], v[152:155], v[192:195], v[8:11]
	s_barrier
	ds_read_b128 v[108:111], v175
	ds_read_b128 v[132:135], v175 offset:1024
	ds_read_b128 v[136:139], v175 offset:2048
	ds_read_b128 v[152:155], v175 offset:3072
	s_add_u32 s12, s12, 0x80080
	s_addc_u32 s13, s13, 0
	s_add_i32 s14, s14, s26
	s_mov_b32 m0, s14
	s_nop 0
	global_load_lds_dwordx4 v140, s[12:13]
	s_add_i32 m0, s14, 0x2000
	s_nop 0
	global_load_lds_dwordx4 v142, s[12:13]
	s_waitcnt vmcnt(6)
	s_barrier
	v_mfma_f32_16x16x32_bf16 v[60:63], v[196:199], v[156:159], v[60:63]
	v_mfma_f32_16x16x32_bf16 v[56:59], v[204:207], v[156:159], v[56:59]
	s_add_i32 s53, s53, 2
	s_add_u32 s2, s2, 0x100
	s_addc_u32 s3, s3, 0
	s_add_u32 s44, s44, 0x100
	s_addc_u32 s45, s45, 0
	s_cmp_gt_u32 s53, 29
	v_mfma_f32_16x16x32_bf16 v[44:47], v[196:199], v[164:167], v[44:47]
	v_mfma_f32_16x16x32_bf16 v[40:43], v[204:207], v[164:167], v[40:43]
	v_mfma_f32_16x16x32_bf16 v[36:39], v[196:199], v[180:183], v[36:39]
	v_mfma_f32_16x16x32_bf16 v[32:35], v[204:207], v[180:183], v[32:35]
	v_mfma_f32_16x16x32_bf16 v[4:7], v[196:199], v[188:191], v[4:7]
	v_mfma_f32_16x16x32_bf16 v[0:3], v[204:207], v[188:191], v[0:3]
	v_mfma_f32_16x16x32_bf16 v[60:63], v[200:203], v[160:163], v[60:63]
	v_mfma_f32_16x16x32_bf16 v[56:59], v[210:213], v[160:163], v[56:59]
	v_mfma_f32_16x16x32_bf16 v[44:47], v[200:203], v[168:171], v[44:47]
	v_mfma_f32_16x16x32_bf16 v[40:43], v[210:213], v[168:171], v[40:43]
	v_mfma_f32_16x16x32_bf16 v[36:39], v[200:203], v[184:187], v[36:39]
	v_mfma_f32_16x16x32_bf16 v[32:35], v[210:213], v[184:187], v[32:35]
	v_mfma_f32_16x16x32_bf16 v[4:7], v[200:203], v[192:195], v[4:7]
	v_mfma_f32_16x16x32_bf16 v[0:3], v[210:213], v[192:195], v[0:3]
	s_barrier
	s_cbranch_scc0 .LBB0_777
	s_waitcnt lgkmcnt(0)
	v_mbcnt_lo_u32_b32 v108, -1, 0
	v_mbcnt_hi_u32_b32 v108, -1, v108
	s_movk_i32 s3, 0x1600
	v_ashrrev_i32_e32 v132, 4, v108
	v_and_b32_e32 v179, 15, v108
	s_lshl_b32 s12, s8, 7
	v_lshl_add_u32 v164, v132, 4, v179
	v_lshrrev_b32_e32 v108, 5, v164
	v_mul_lo_u32 v108, v108, s3
	v_add_u32_e32 v108, s12, v108
	v_and_b32_e32 v109, 31, v164
	v_readlane_b32 s3, v254, 19
	s_lshl_b32 s2, s10, 8
	s_add_i32 s2, s2, s22
	v_or3_b32 v108, v108, v109, s3
	v_ashrrev_i32_e32 v109, 31, v108
	v_lshlrev_b64 v[108:109], 2, v[108:109]
	v_lshl_add_u64 v[110:111], s[76:77], 0, v[108:109]
	global_load_dword v165, v[110:111], off
	v_lshl_add_u64 v[110:111], s[34:35], 0, v[108:109]
	global_load_dword v166, v[110:111], off
	v_lshl_add_u64 v[110:111], s[48:49], 0, v[108:109]
	v_lshl_add_u64 v[108:109], s[78:79], 0, v[108:109]
	global_load_dword v167, v[110:111], off
	global_load_dword v168, v[108:109], off
	v_mov_b32_e32 v108, s25
	ds_read_b32 v108, v108
	v_add_u32_e32 v152, s2, v179
	v_lshl_add_u32 v155, v179, 2, s21
	s_waitcnt lgkmcnt(0)
	v_readfirstlane_b32 s2, v108
	s_cmp_eq_u32 s2, s10
	s_cbranch_scc1 .LBB0_798
	v_lshlrev_b32_e32 v108, 3, v132
	v_ashrrev_i32_e32 v109, 31, v108
	v_ashrrev_i32_e32 v153, 31, v152
	v_lshl_add_u64 v[108:109], v[108:109], 2, s[16:17]
	v_lshlrev_b64 v[110:111], 7, v[152:153]
	v_lshl_add_u64 v[110:111], v[108:109], 0, v[110:111]
	s_mov_b64 s[2:3], 0x1000
	v_lshl_add_u64 v[248:249], v[110:111], 0, s[2:3]
	s_mov_b64 s[2:3], 0x4000
	v_lshl_add_u64 v[134:135], v[110:111], 0, s[2:3]
	s_mov_b64 s[2:3], 0x5000
	v_lshl_add_u64 v[108:109], v[110:111], 0, s[2:3]
	global_load_dwordx4 v[180:183], v[110:111], off
	global_load_dwordx4 v[184:187], v[110:111], off offset:16
	global_load_dwordx4 v[188:191], v[110:111], off offset:2048
	global_load_dwordx4 v[192:195], v[110:111], off offset:2064
	global_load_dwordx4 v[196:199], v[248:249], off
	global_load_dwordx4 v[200:203], v[248:249], off offset:16
	global_load_dwordx4 v[204:207], v[248:249], off offset:2048
	global_load_dwordx4 v[210:213], v[248:249], off offset:2064
	global_load_dwordx4 v[214:217], v[134:135], off
	global_load_dwordx4 v[218:221], v[134:135], off offset:16
	global_load_dwordx4 v[222:225], v[134:135], off offset:2048
	global_load_dwordx4 v[226:229], v[134:135], off offset:2064
	global_load_dwordx4 v[230:233], v[108:109], off
	global_load_dwordx4 v[234:237], v[108:109], off offset:16
	global_load_dwordx4 v[238:241], v[108:109], off offset:2048
	global_load_dwordx4 v[242:245], v[108:109], off offset:2064
	v_and_b32_e32 v250, 64, v209
	v_xor_b32_e32 v133, 16, v209
	v_add_u32_e32 v250, 64, v250
	v_cmp_lt_i32_e32 vcc, v133, v250
	v_xor_b32_e32 v110, 32, v209
	s_nop 1
	v_cndmask_b32_e32 v133, v209, v133, vcc
	v_cmp_eq_u32_e64 s[42:43], 0, v132
	v_lshlrev_b32_e32 v133, 2, v133
	v_cmp_lt_i32_e32 vcc, v110, v250
	s_nop 1
	v_cndmask_b32_e32 v110, v209, v110, vcc
	v_lshlrev_b32_e32 v110, 2, v110
	s_waitcnt vmcnt(14)
; __device__ __forceinline__ float row_rstd(const float* ssq, int row, int fq) {
;     const f32x4 a = *(const f32x4*)(ssq + (size_t)row * 32 + 8 * fq), b = *(const f32x4*)(ssq + (size_t)row * 32 + 8 * fq + 4);
;     float t = ((a[0] + a[1]) + (a[2] + a[3])) + ((b[0] + b[1]) + (b[2] + b[3]));
;     t += __shfl_xor(t, 16); t += __shfl_xor(t, 32);
;     return rsqrtf(t * (1.0f / 2048.0f) + EPS);
; }
;     __device__ __forceinline__ void operator()(f32x4 (&acc)[2][2][4][2], const Unit& u, int wr, int wc, int fr, int fq) const {
;     ...
;                 for (int ai = 0; ai < 2; ++ai)
; #pragma unroll
;                     for (int m = 0; m < 4; ++m) { const float r_ = row_rstd(ssq_in, rowt + ai * HALF + m * 16, fq); if (fq == 0) myr[(ai * 4 + m) * 16 + fr] = r_; }
;                 if (fq == 0 && fr == 0) *mypm = u.pm;
;                 asm volatile("s_waitcnt lgkmcnt(0)" ::: "memory");
	v_add_f32_e32 v180, v180, v181
	v_add_f32_e32 v181, v182, v183
	v_add_f32_e32 v184, v184, v185
	v_add_f32_e32 v185, v186, v187
	v_add_f32_e32 v180, v180, v181
	v_add_f32_e32 v184, v184, v185
	v_add_f32_e32 v156, v180, v184
	s_waitcnt vmcnt(12)
	v_add_f32_e32 v188, v188, v189
	v_add_f32_e32 v189, v190, v191
	v_add_f32_e32 v192, v192, v193
	v_add_f32_e32 v193, v194, v195
	v_add_f32_e32 v188, v188, v189
	v_add_f32_e32 v192, v192, v193
	v_add_f32_e32 v157, v188, v192
	s_waitcnt vmcnt(10)
	v_add_f32_e32 v196, v196, v197
	v_add_f32_e32 v197, v198, v199
	v_add_f32_e32 v200, v200, v201
	v_add_f32_e32 v201, v202, v203
	v_add_f32_e32 v196, v196, v197
	v_add_f32_e32 v200, v200, v201
	v_add_f32_e32 v158, v196, v200
	s_waitcnt vmcnt(8)
	v_add_f32_e32 v204, v204, v205
	v_add_f32_e32 v205, v206, v207
	v_add_f32_e32 v210, v210, v211
	v_add_f32_e32 v211, v212, v213
	v_add_f32_e32 v204, v204, v205
	v_add_f32_e32 v210, v210, v211
	v_add_f32_e32 v159, v204, v210
	s_waitcnt vmcnt(6)
	v_add_f32_e32 v214, v214, v215
	v_add_f32_e32 v215, v216, v217
	v_add_f32_e32 v218, v218, v219
	v_add_f32_e32 v219, v220, v221
	v_add_f32_e32 v214, v214, v215
	v_add_f32_e32 v218, v218, v219
	v_add_f32_e32 v160, v214, v218
	s_waitcnt vmcnt(4)
	v_add_f32_e32 v222, v222, v223
	v_add_f32_e32 v223, v224, v225
	v_add_f32_e32 v226, v226, v227
	v_add_f32_e32 v227, v228, v229
	v_add_f32_e32 v222, v222, v223
	v_add_f32_e32 v226, v226, v227
	v_add_f32_e32 v161, v222, v226
	s_waitcnt vmcnt(2)
	v_add_f32_e32 v230, v230, v231
	v_add_f32_e32 v231, v232, v233
	v_add_f32_e32 v234, v234, v235
	v_add_f32_e32 v235, v236, v237
	v_add_f32_e32 v230, v230, v231
	v_add_f32_e32 v234, v234, v235
	v_add_f32_e32 v162, v230, v234
	s_waitcnt vmcnt(0)
	v_add_f32_e32 v238, v238, v239
	v_add_f32_e32 v239, v240, v241
	v_add_f32_e32 v242, v242, v243
	v_add_f32_e32 v243, v244, v245
	v_add_f32_e32 v238, v238, v239
	v_add_f32_e32 v242, v242, v243
	v_add_f32_e32 v163, v238, v242
	ds_bpermute_b32 v136, v133, v156
	ds_bpermute_b32 v137, v133, v157
	ds_bpermute_b32 v138, v133, v158
	ds_bpermute_b32 v139, v133, v159
	ds_bpermute_b32 v108, v133, v160
	ds_bpermute_b32 v109, v133, v161
	ds_bpermute_b32 v246, v133, v162
	ds_bpermute_b32 v247, v133, v163
	s_waitcnt lgkmcnt(0)
	v_add_f32_e32 v156, v156, v136
	v_add_f32_e32 v157, v157, v137
	v_add_f32_e32 v158, v158, v138
	v_add_f32_e32 v159, v159, v139
	v_add_f32_e32 v160, v160, v108
	v_add_f32_e32 v161, v161, v109
	v_add_f32_e32 v162, v162, v246
	v_add_f32_e32 v163, v163, v247
	ds_bpermute_b32 v136, v110, v156
	ds_bpermute_b32 v137, v110, v157
	ds_bpermute_b32 v138, v110, v158
	ds_bpermute_b32 v139, v110, v159
	ds_bpermute_b32 v108, v110, v160
	ds_bpermute_b32 v109, v110, v161
	ds_bpermute_b32 v246, v110, v162
	ds_bpermute_b32 v247, v110, v163
	s_and_saveexec_b64 s[2:3], s[42:43]
	s_cbranch_execz .Lrs_skip
	s_waitcnt lgkmcnt(0)
	v_add_f32_e32 v156, v156, v136
	v_fmamk_f32 v156, v156, 0x3a000000, v178
	v_mul_f32_e32 v136, 0x4b800000, v156
	v_cmp_gt_f32_e32 vcc, s65, v156
	s_nop 1
	v_cndmask_b32_e32 v156, v156, v136, vcc
	v_rsq_f32_e32 v156, v156
	s_nop 0
	v_mul_f32_e32 v136, 0x45800000, v156
	v_cndmask_b32_e32 v156, v156, v136, vcc
	ds_write_b32 v155, v156
	v_add_f32_e32 v157, v157, v137
	v_fmamk_f32 v157, v157, 0x3a000000, v178
	v_mul_f32_e32 v137, 0x4b800000, v157
	v_cmp_gt_f32_e32 vcc, s65, v157
	s_nop 1
	v_cndmask_b32_e32 v157, v157, v137, vcc
	v_rsq_f32_e32 v157, v157
	s_nop 0
	v_mul_f32_e32 v137, 0x45800000, v157
	v_cndmask_b32_e32 v157, v157, v137, vcc
	ds_write_b32 v155, v157 offset:64
	v_add_f32_e32 v158, v158, v138
	v_fmamk_f32 v158, v158, 0x3a000000, v178
	v_mul_f32_e32 v138, 0x4b800000, v158
	v_cmp_gt_f32_e32 vcc, s65, v158
	s_nop 1
	v_cndmask_b32_e32 v158, v158, v138, vcc
	v_rsq_f32_e32 v158, v158
	s_nop 0
	v_mul_f32_e32 v138, 0x45800000, v158
	v_cndmask_b32_e32 v158, v158, v138, vcc
	ds_write_b32 v155, v158 offset:128
	v_add_f32_e32 v159, v159, v139
	v_fmamk_f32 v159, v159, 0x3a000000, v178
	v_mul_f32_e32 v139, 0x4b800000, v159
	v_cmp_gt_f32_e32 vcc, s65, v159
	s_nop 1
	v_cndmask_b32_e32 v159, v159, v139, vcc
	v_rsq_f32_e32 v159, v159
	s_nop 0
	v_mul_f32_e32 v139, 0x45800000, v159
	v_cndmask_b32_e32 v159, v159, v139, vcc
	ds_write_b32 v155, v159 offset:192
	v_add_f32_e32 v160, v160, v108
	v_fmamk_f32 v160, v160, 0x3a000000, v178
	v_mul_f32_e32 v108, 0x4b800000, v160
	v_cmp_gt_f32_e32 vcc, s65, v160
	s_nop 1
	v_cndmask_b32_e32 v160, v160, v108, vcc
	v_rsq_f32_e32 v160, v160
	s_nop 0
	v_mul_f32_e32 v108, 0x45800000, v160
	v_cndmask_b32_e32 v160, v160, v108, vcc
	ds_write_b32 v155, v160 offset:256
	v_add_f32_e32 v161, v161, v109
	v_fmamk_f32 v161, v161, 0x3a000000, v178
	v_mul_f32_e32 v109, 0x4b800000, v161
	v_cmp_gt_f32_e32 vcc, s65, v161
	s_nop 1
	v_cndmask_b32_e32 v161, v161, v109, vcc
	v_rsq_f32_e32 v161, v161
	s_nop 0
	v_mul_f32_e32 v109, 0x45800000, v161
	v_cndmask_b32_e32 v161, v161, v109, vcc
	ds_write_b32 v155, v161 offset:320
	v_add_f32_e32 v162, v162, v246
	v_fmamk_f32 v162, v162, 0x3a000000, v178
	v_mul_f32_e32 v246, 0x4b800000, v162
	v_cmp_gt_f32_e32 vcc, s65, v162
	s_nop 1
	v_cndmask_b32_e32 v162, v162, v246, vcc
	v_rsq_f32_e32 v162, v162
	s_nop 0
	v_mul_f32_e32 v246, 0x45800000, v162
	v_cndmask_b32_e32 v162, v162, v246, vcc
	ds_write_b32 v155, v162 offset:384
	v_add_f32_e32 v163, v163, v247
	v_fmamk_f32 v163, v163, 0x3a000000, v178
	v_mul_f32_e32 v247, 0x4b800000, v163
	v_cmp_gt_f32_e32 vcc, s65, v163
	s_nop 1
	v_cndmask_b32_e32 v163, v163, v247, vcc
	v_rsq_f32_e32 v163, v163
	s_nop 0
	v_mul_f32_e32 v247, 0x45800000, v163
	v_cndmask_b32_e32 v163, v163, v247, vcc
	ds_write_b32 v155, v163 offset:448
.Lrs_skip:
	s_or_b64 exec, exec, s[2:3]
	v_or_b32_e32 v108, v132, v179
	v_cmp_eq_u32_e32 vcc, 0, v108
	s_and_saveexec_b64 s[2:3], vcc
	s_cbranch_execz .Lrs_done
	v_mov_b32_e32 v108, s25
	v_mov_b32_e32 v109, s10
	ds_write_b32 v108, v109

; __device__ void conv_fixup(const float* uedge, const float* cw, const float* cb, bf16_t* act, int pm, const int WID) {
;     const bool hp = (pm & 15) != 0;
;     const float* e = uedge + (size_t)pm * 4 * FF2; const float* ep = uedge + (size_t)(pm - 1) * 4 * FF2;
;     for (int idx = TID_X; idx < 2 * FF; idx += 512) {
;         const int r = idx / FF, j = idx - r * FF; const int cg_ = 256 * (j >> 7) + (j & 127);
;         float uc[2];
; #pragma unroll
;         for (int bj = 0; bj < 2; ++bj) { const int cc = cg_ + 128 * bj, no = j + FF * bj;
;             const float u0 = e[cc], u1 = e[FF2 + cc];
;             const float p254 = hp ? ep[2 * FF2 + cc] : 0.f, p255 = hp ? ep[3 * FF2 + cc] : 0.f;
;             const float c0 = cw[no], c1 = cw[FF2 + no], c2 = cw[2 * FF2 + no], bb = cb[no];
;             uc[bj] = (r == 0) ? (bb + c2 * u0 + c1 * p255 + c0 * p254) : (bb + c2 * u1 + c1 * u0 + c0 * p255); }
.LBB0_880:
	s_cmp_eq_u32 s18, s10
	s_cbranch_scc1 .LBB0_871
	v_mbcnt_lo_u32_b32 v20, -1, 0
	v_mbcnt_hi_u32_b32 v20, -1, v20
	s_lshl_b32 s2, s18, 2
	s_and_b32 s3, s18, 15
	s_cmp_lg_u32 s3, 0
	s_cselect_b32 s11, -2, 0
	s_lshl_b32 s12, s18, 8
	s_mov_b32 s13, 0
	v_add_u32_e32 v20, s92, v20
.Lfx_batch:
	s_add_i32 s14, s13, 0
	s_lshl_b32 s14, s14, 9
	v_add_u32_e32 v80, s14, v20
	v_min_u32_e32 v80, 0xaff, v80
	v_cmp_lt_u32_e32 vcc, 0x57f, v80
	s_nop 1
	v_cndmask_b32_e64 v81, 0, 1, vcc
	v_mul_u32_u24_e32 v94, 0x580, v81
	v_sub_u32_e32 v82, v80, v94
	v_lshlrev_b32_e32 v82, 2, v82
	v_and_b32_e32 v94, 0xffffff80, v82
	v_and_b32_e32 v83, 0x7f, v82
	v_lshl_or_b32 v83, v94, 1, v83
	v_lshlrev_b32_e32 v83, 2, v83
	v_add_u32_e32 v87, s2, v81
	v_mul_u32_u24_e32 v87, 0xb000, v87
	v_add_u32_e32 v87, v87, v83
	v_subrev_u32_e32 v86, 1, v81
	v_max_i32_e32 v86, s11, v86
	v_add_u32_e32 v86, s2, v86
	v_mul_u32_u24_e32 v86, 0xb000, v86
	v_add_u32_e32 v86, v86, v83
	v_subrev_u32_e32 v85, 2, v81
	v_max_i32_e32 v85, s11, v85
	v_add_u32_e32 v85, s2, v85
	v_mul_u32_u24_e32 v85, 0xb000, v85
	v_add_u32_e32 v85, v85, v83
	v_lshlrev_b32_e32 v88, 2, v82
	v_add_u32_e32 v89, 0xb000, v88
	v_add_u32_e32 v90, 0x16000, v88
	v_add_u32_e32 v91, 0x5800, v88
	v_add_u32_e32 v92, 0x10800, v88
	v_add_u32_e32 v93, 0x1b800, v88
	v_add_u32_e32 v84, s12, v81
	v_mul_u32_u24_e32 v84, 0x1600, v84
	v_add_lshl_u32 v84, v84, v82, 1
	global_load_dwordx4 v[24:27], v87, s[30:31]
	global_load_dwordx4 v[28:31], v87, s[30:31] offset:512
	global_load_dwordx4 v[32:35], v86, s[30:31]
	global_load_dwordx4 v[36:39], v86, s[30:31] offset:512
	global_load_dwordx4 v[40:43], v85, s[30:31]
	global_load_dwordx4 v[44:47], v85, s[30:31] offset:512
	global_load_dwordx4 v[48:51], v88, s[76:77]
	global_load_dwordx4 v[52:55], v91, s[76:77]
	global_load_dwordx4 v[56:59], v89, s[76:77]
	global_load_dwordx4 v[60:63], v92, s[76:77]
	global_load_dwordx4 v[64:67], v90, s[76:77]
	global_load_dwordx4 v[68:71], v93, s[76:77]
	global_load_dwordx4 v[72:75], v88, s[78:79]
	global_load_dwordx4 v[76:79], v91, s[78:79]
	s_add_i32 s14, s13, 1
	s_lshl_b32 s14, s14, 9
	v_add_u32_e32 v152, s14, v20
	v_min_u32_e32 v152, 0xaff, v152
	v_cmp_lt_u32_e32 vcc, 0x57f, v152
	s_nop 1
	v_cndmask_b32_e64 v153, 0, 1, vcc
	v_mul_u32_u24_e32 v166, 0x580, v153
	v_sub_u32_e32 v154, v152, v166
	v_lshlrev_b32_e32 v154, 2, v154
	v_and_b32_e32 v166, 0xffffff80, v154
	v_and_b32_e32 v155, 0x7f, v154
	v_lshl_or_b32 v155, v166, 1, v155
	v_lshlrev_b32_e32 v155, 2, v155
	v_add_u32_e32 v159, s2, v153
	v_mul_u32_u24_e32 v159, 0xb000, v159
	v_add_u32_e32 v159, v159, v155
	v_subrev_u32_e32 v158, 1, v153
	v_max_i32_e32 v158, s11, v158
	v_add_u32_e32 v158, s2, v158
	v_mul_u32_u24_e32 v158, 0xb000, v158
	v_add_u32_e32 v158, v158, v155
	v_subrev_u32_e32 v157, 2, v153
	v_max_i32_e32 v157, s11, v157
	v_add_u32_e32 v157, s2, v157
	v_mul_u32_u24_e32 v157, 0xb000, v157
	v_add_u32_e32 v157, v157, v155
	v_lshlrev_b32_e32 v160, 2, v154
	v_add_u32_e32 v161, 0xb000, v160
	v_add_u32_e32 v162, 0x16000, v160
	v_add_u32_e32 v163, 0x5800, v160
	v_add_u32_e32 v164, 0x10800, v160
	v_add_u32_e32 v165, 0x1b800, v160
	v_add_u32_e32 v156, s12, v153
	v_mul_u32_u24_e32 v156, 0x1600, v156
	v_add_lshl_u32 v156, v156, v154, 1
	global_load_dwordx4 v[96:99], v159, s[30:31]
	global_load_dwordx4 v[100:103], v159, s[30:31] offset:512
	global_load_dwordx4 v[104:107], v158, s[30:31]
	global_load_dwordx4 v[108:111], v158, s[30:31] offset:512
	global_load_dwordx4 v[112:115], v157, s[30:31]
	global_load_dwordx4 v[116:119], v157, s[30:31] offset:512
	global_load_dwordx4 v[120:123], v160, s[76:77]
	global_load_dwordx4 v[124:127], v163, s[76:77]
	global_load_dwordx4 v[128:131], v161, s[76:77]
	global_load_dwordx4 v[132:135], v164, s[76:77]
	global_load_dwordx4 v[136:139], v162, s[76:77]
	global_load_dwordx4 v[140:143], v165, s[76:77]
	global_load_dwordx4 v[144:147], v160, s[78:79]
	global_load_dwordx4 v[148:151], v163, s[78:79]
	s_add_i32 s14, s13, 2
	s_lshl_b32 s14, s14, 9
	v_add_u32_e32 v228, s14, v20
	v_min_u32_e32 v228, 0xaff, v228
	v_cmp_lt_u32_e32 vcc, 0x57f, v228
	s_nop 1
	v_cndmask_b32_e64 v229, 0, 1, vcc
	v_mul_u32_u24_e32 v242, 0x580, v229
	v_sub_u32_e32 v230, v228, v242
	v_lshlrev_b32_e32 v230, 2, v230
	v_and_b32_e32 v242, 0xffffff80, v230
	v_and_b32_e32 v231, 0x7f, v230
	v_lshl_or_b32 v231, v242, 1, v231
	v_lshlrev_b32_e32 v231, 2, v231
	v_add_u32_e32 v235, s2, v229
	v_mul_u32_u24_e32 v235, 0xb000, v235
	v_add_u32_e32 v235, v235, v231
	v_subrev_u32_e32 v234, 1, v229
	v_max_i32_e32 v234, s11, v234
	v_add_u32_e32 v234, s2, v234
	v_mul_u32_u24_e32 v234, 0xb000, v234
	v_add_u32_e32 v234, v234, v231
	v_subrev_u32_e32 v233, 2, v229
	v_max_i32_e32 v233, s11, v233
	v_add_u32_e32 v233, s2, v233
	v_mul_u32_u24_e32 v233, 0xb000, v233
	v_add_u32_e32 v233, v233, v231
	v_lshlrev_b32_e32 v236, 2, v230
	v_add_u32_e32 v237, 0xb000, v236
	v_add_u32_e32 v238, 0x16000, v236
	v_add_u32_e32 v239, 0x5800, v236
	v_add_u32_e32 v240, 0x10800, v236
	v_add_u32_e32 v241, 0x1b800, v236
	v_add_u32_e32 v232, s12, v229
	v_mul_u32_u24_e32 v232, 0x1600, v232
	v_add_lshl_u32 v232, v232, v230, 1
	global_load_dwordx4 v[168:171], v235, s[30:31]
	global_load_dwordx4 v[172:175], v235, s[30:31] offset:512
	global_load_dwordx4 v[176:179], v234, s[30:31]
	global_load_dwordx4 v[180:183], v234, s[30:31] offset:512
	global_load_dwordx4 v[184:187], v233, s[30:31]
	global_load_dwordx4 v[188:191], v233, s[30:31] offset:512
	global_load_dwordx4 v[192:195], v236, s[76:77]
	global_load_dwordx4 v[196:199], v239, s[76:77]
	global_load_dwordx4 v[200:203], v237, s[76:77]
	global_load_dwordx4 v[204:207], v240, s[76:77]
	global_load_dwordx4 v[212:215], v238, s[76:77]
	global_load_dwordx4 v[216:219], v241, s[76:77]
	global_load_dwordx4 v[220:223], v236, s[78:79]
	global_load_dwordx4 v[224:227], v239, s[78:79]
	s_waitcnt vmcnt(28)
	s_cmp_lg_u32 s11, 0
	s_cbranch_scc1 .Lfx_nz0
	v_cmp_gt_u32_e32 vcc, 1, v81
	s_nop 1
	v_cndmask_b32_e64 v32, v32, 0, vcc
	v_cndmask_b32_e64 v33, v33, 0, vcc
	v_cndmask_b32_e64 v34, v34, 0, vcc
	v_cndmask_b32_e64 v35, v35, 0, vcc
	v_cndmask_b32_e64 v36, v36, 0, vcc
	v_cndmask_b32_e64 v37, v37, 0, vcc
	v_cndmask_b32_e64 v38, v38, 0, vcc
	v_cndmask_b32_e64 v39, v39, 0, vcc
	v_mov_b32_e32 v40, 0
	v_mov_b32_e32 v41, 0
	v_mov_b32_e32 v42, 0
	v_mov_b32_e32 v43, 0
	v_mov_b32_e32 v44, 0
	v_mov_b32_e32 v45, 0
	v_mov_b32_e32 v46, 0
	v_mov_b32_e32 v47, 0
; __device__ __forceinline__ unsigned cvt_pk_bf16(float lo, float hi) { unsigned r; asm volatile("v_cvt_pk_bf16_f32 %0, %1, %2" : "=v"(r) : "v"(lo), "v"(hi)); return r; }
; __device__ __forceinline__ float sigmoidf_(float x) { return __builtin_amdgcn_rcpf(1.0f + __expf(-x)); }
; __device__ void conv_fixup(const float* uedge, const float* cw, const float* cb, bf16_t* act, int pm, const int WID) {
;     ...
;         for (int bj = 0; bj < 2; ++bj) { const int cc = cg_ + 128 * bj, no = j + FF * bj;
;             const float u0 = e[cc], u1 = e[FF2 + cc];
;             const float p254 = hp ? ep[2 * FF2 + cc] : 0.f, p255 = hp ? ep[3 * FF2 + cc] : 0.f;
;             const float c0 = cw[no], c1 = cw[FF2 + no], c2 = cw[2 * FF2 + no], bb = cb[no];
;             uc[bj] = (r == 0) ? (bb + c2 * u0 + c1 * p255 + c0 * p254) : (bb + c2 * u1 + c1 * u0 + c0 * p255); }
;         const float a = uc[0] * sigmoidf_(uc[0]) * uc[1];
;         act[(size_t)(pm * 256 + r) * FF + j] = (bf16_t)(cvt_pk_bf16(a, 0.f) & 0xffff);
.Lfx_nz0:
	v_pk_fma_f32 v[72:73], v[24:25], v[64:65], v[72:73]
	v_pk_fma_f32 v[74:75], v[26:27], v[66:67], v[74:75]
	v_pk_fma_f32 v[72:73], v[32:33], v[56:57], v[72:73]
	v_pk_fma_f32 v[74:75], v[34:35], v[58:59], v[74:75]
	v_pk_fma_f32 v[72:73], v[40:41], v[48:49], v[72:73]
	v_pk_fma_f32 v[74:75], v[42:43], v[50:51], v[74:75]
	v_pk_fma_f32 v[76:77], v[28:29], v[68:69], v[76:77]
	v_pk_fma_f32 v[78:79], v[30:31], v[70:71], v[78:79]
	v_pk_fma_f32 v[76:77], v[36:37], v[60:61], v[76:77]
	v_pk_fma_f32 v[78:79], v[38:39], v[62:63], v[78:79]
	v_pk_mul_f32 v[44:45], v[44:45], v[52:53]
	v_pk_mul_f32 v[46:47], v[46:47], v[54:55]
	v_pk_add_f32 v[76:77], v[44:45], v[76:77]
	v_pk_add_f32 v[78:79], v[46:47], v[78:79]
	v_mul_f32_e32 v24, 0xbfb8aa3b, v72
	v_mul_f32_e32 v25, 0xbfb8aa3b, v73
	v_mul_f32_e32 v26, 0xbfb8aa3b, v74
	v_mul_f32_e32 v27, 0xbfb8aa3b, v75
	v_exp_f32_e32 v24, v24
	v_exp_f32_e32 v25, v25
	v_exp_f32_e32 v26, v26
	v_exp_f32_e32 v27, v27
	v_add_f32_e32 v24, 1.0, v24
	v_add_f32_e32 v25, 1.0, v25
	v_add_f32_e32 v26, 1.0, v26
	v_add_f32_e32 v27, 1.0, v27
	v_rcp_f32_e32 v24, v24
	v_rcp_f32_e32 v25, v25
	v_rcp_f32_e32 v26, v26
	v_rcp_f32_e32 v27, v27
	v_mul_f32_e32 v72, v72, v24
	v_mul_f32_e32 v73, v73, v25
	v_mul_f32_e32 v74, v74, v26
	v_mul_f32_e32 v75, v75, v27
	v_mul_f32_e32 v72, v72, v76
	v_mul_f32_e32 v73, v73, v77
	v_mul_f32_e32 v74, v74, v78
	v_mul_f32_e32 v75, v75, v79
	v_cvt_pk_bf16_f32 v72, v72, v73
	v_cvt_pk_bf16_f32 v73, v74, v75
	s_add_i32 s14, s13, 0
	s_lshl_b32 s14, s14, 9
	v_add_u32_e32 v94, s14, v20
	v_cmp_gt_u32_e32 vcc, 0xb00, v94
	s_and_saveexec_b64 s[8:9], vcc
	global_store_dwordx2 v84, v[72:73], s[0:1]
	s_or_b64 exec, exec, s[8:9]
	s_waitcnt vmcnt(14)
	s_cmp_lg_u32 s11, 0
	s_cbranch_scc1 .Lfx_nz1
	v_cmp_gt_u32_e32 vcc, 1, v153
	s_nop 1
	v_cndmask_b32_e64 v104, v104, 0, vcc
	v_cndmask_b32_e64 v105, v105, 0, vcc
	v_cndmask_b32_e64 v106, v106, 0, vcc
	v_cndmask_b32_e64 v107, v107, 0, vcc
	v_cndmask_b32_e64 v108, v108, 0, vcc
	v_cndmask_b32_e64 v109, v109, 0, vcc
	v_cndmask_b32_e64 v110, v110, 0, vcc
	v_cndmask_b32_e64 v111, v111, 0, vcc
	v_mov_b32_e32 v112, 0
	v_mov_b32_e32 v113, 0
	v_mov_b32_e32 v114, 0
	v_mov_b32_e32 v115, 0
	v_mov_b32_e32 v116, 0
	v_mov_b32_e32 v117, 0
	v_mov_b32_e32 v118, 0
	v_mov_b32_e32 v119, 0
.Lfx_nz1:
	v_pk_fma_f32 v[144:145], v[96:97], v[136:137], v[144:145]
	v_pk_fma_f32 v[146:147], v[98:99], v[138:139], v[146:147]
	v_pk_fma_f32 v[144:145], v[104:105], v[128:129], v[144:145]
	v_pk_fma_f32 v[146:147], v[106:107], v[130:131], v[146:147]
	v_pk_fma_f32 v[144:145], v[112:113], v[120:121], v[144:145]
	v_pk_fma_f32 v[146:147], v[114:115], v[122:123], v[146:147]
	v_pk_fma_f32 v[148:149], v[100:101], v[140:141], v[148:149]
	v_pk_fma_f32 v[150:151], v[102:103], v[142:143], v[150:151]
	v_pk_fma_f32 v[148:149], v[108:109], v[132:133], v[148:149]
	v_pk_fma_f32 v[150:151], v[110:111], v[134:135], v[150:151]
	v_pk_mul_f32 v[116:117], v[116:117], v[124:125]
	v_pk_mul_f32 v[118:119], v[118:119], v[126:127]
	v_pk_add_f32 v[148:149], v[116:117], v[148:149]
	v_pk_add_f32 v[150:151], v[118:119], v[150:151]
	v_mul_f32_e32 v96, 0xbfb8aa3b, v144
	v_mul_f32_e32 v97, 0xbfb8aa3b, v145
	v_mul_f32_e32 v98, 0xbfb8aa3b, v146
	v_mul_f32_e32 v99, 0xbfb8aa3b, v147
	v_exp_f32_e32 v96, v96
	v_exp_f32_e32 v97, v97
	v_exp_f32_e32 v98, v98
	v_exp_f32_e32 v99, v99
	v_add_f32_e32 v96, 1.0, v96
	v_add_f32_e32 v97, 1.0, v97
	v_add_f32_e32 v98, 1.0, v98
	v_add_f32_e32 v99, 1.0, v99
	v_rcp_f32_e32 v96, v96
	v_rcp_f32_e32 v97, v97
	v_rcp_f32_e32 v98, v98
	v_rcp_f32_e32 v99, v99
	v_mul_f32_e32 v144, v144, v96
	v_mul_f32_e32 v145, v145, v97
	v_mul_f32_e32 v146, v146, v98
	v_mul_f32_e32 v147, v147, v99
	v_mul_f32_e32 v144, v144, v148
	v_mul_f32_e32 v145, v145, v149
	v_mul_f32_e32 v146, v146, v150
	v_mul_f32_e32 v147, v147, v151
	v_cvt_pk_bf16_f32 v144, v144, v145
	v_cvt_pk_bf16_f32 v145, v146, v147
	s_add_i32 s14, s13, 1
	s_lshl_b32 s14, s14, 9
	v_add_u32_e32 v166, s14, v20
	v_cmp_gt_u32_e32 vcc, 0xb00, v166
	s_and_saveexec_b64 s[8:9], vcc
	global_store_dwordx2 v156, v[144:145], s[0:1]
	s_or_b64 exec, exec, s[8:9]
	s_waitcnt vmcnt(0)
	s_cmp_lg_u32 s11, 0
	s_cbranch_scc1 .Lfx_nz2
	v_cmp_gt_u32_e32 vcc, 1, v229
	s_nop 1
	v_cndmask_b32_e64 v176, v176, 0, vcc
	v_cndmask_b32_e64 v177, v177, 0, vcc
	v_cndmask_b32_e64 v178, v178, 0, vcc
	v_cndmask_b32_e64 v179, v179, 0, vcc
	v_cndmask_b32_e64 v180, v180, 0, vcc
	v_cndmask_b32_e64 v181, v181, 0, vcc
	v_cndmask_b32_e64 v182, v182, 0, vcc
	v_cndmask_b32_e64 v183, v183, 0, vcc
	v_mov_b32_e32 v184, 0
	v_mov_b32_e32 v185, 0
	v_mov_b32_e32 v186, 0
	v_mov_b32_e32 v187, 0
	v_mov_b32_e32 v188, 0
	v_mov_b32_e32 v189, 0
	v_mov_b32_e32 v190, 0
	v_mov_b32_e32 v191, 0
.Lfx_nz2:
	v_pk_fma_f32 v[220:221], v[168:169], v[212:213], v[220:221]
	v_pk_fma_f32 v[222:223], v[170:171], v[214:215], v[222:223]
	v_pk_fma_f32 v[220:221], v[176:177], v[200:201], v[220:221]
	v_pk_fma_f32 v[222:223], v[178:179], v[202:203], v[222:223]
	v_pk_fma_f32 v[220:221], v[184:185], v[192:193], v[220:221]
	v_pk_fma_f32 v[222:223], v[186:187], v[194:195], v[222:223]
	v_pk_fma_f32 v[224:225], v[172:173], v[216:217], v[224:225]
	v_pk_fma_f32 v[226:227], v[174:175], v[218:219], v[226:227]
	v_pk_fma_f32 v[224:225], v[180:181], v[204:205], v[224:225]
	v_pk_fma_f32 v[226:227], v[182:183], v[206:207], v[226:227]
	v_pk_mul_f32 v[188:189], v[188:189], v[196:197]
	v_pk_mul_f32 v[190:191], v[190:191], v[198:199]
	v_pk_add_f32 v[224:225], v[188:189], v[224:225]
	v_pk_add_f32 v[226:227], v[190:191], v[226:227]
	v_mul_f32_e32 v168, 0xbfb8aa3b, v220
	v_mul_f32_e32 v169, 0xbfb8aa3b, v221
	v_mul_f32_e32 v170, 0xbfb8aa3b, v222
	v_mul_f32_e32 v171, 0xbfb8aa3b, v223
	v_exp_f32_e32 v168, v168
	v_exp_f32_e32 v169, v169
	v_exp_f32_e32 v170, v170
	v_exp_f32_e32 v171, v171
	v_add_f32_e32 v168, 1.0, v168
	v_add_f32_e32 v169, 1.0, v169
	v_add_f32_e32 v170, 1.0, v170
	v_add_f32_e32 v171, 1.0, v171
	v_rcp_f32_e32 v168, v168
	v_rcp_f32_e32 v169, v169
	v_rcp_f32_e32 v170, v170
	v_rcp_f32_e32 v171, v171
	v_mul_f32_e32 v220, v220, v168
	v_mul_f32_e32 v221, v221, v169
	v_mul_f32_e32 v222, v222, v170
	v_mul_f32_e32 v223, v223, v171
	v_mul_f32_e32 v220, v220, v224
	v_mul_f32_e32 v221, v221, v225
	v_mul_f32_e32 v222, v222, v226
	v_mul_f32_e32 v223, v223, v227
	v_cvt_pk_bf16_f32 v220, v220, v221
	v_cvt_pk_bf16_f32 v221, v222, v223
	s_add_i32 s14, s13, 2
	s_lshl_b32 s14, s14, 9
	v_add_u32_e32 v242, s14, v20
	v_cmp_gt_u32_e32 vcc, 0xb00, v242
	s_and_saveexec_b64 s[8:9], vcc
	global_store_dwordx2 v232, v[220:221], s[0:1]
	s_or_b64 exec, exec, s[8:9]
	s_add_i32 s13, s13, 3
	s_cmp_lt_u32 s13, 6
	s_cbranch_scc1 .Lfx_batch
	s_mov_b64 s[8:9], exec
	s_branch .LBB0_870
